# code prefetch windows of the last three seams trimmed so every prefetch load stays inside the kernel's own text section
# baseline (speedup 1.0000x reference)
.Lxb_pf_12:
	s_getpc_b64 s[18:19]
	s_mov_b64 s[22:23], exec
	s_mov_b64 exec, -1
	v_mbcnt_lo_u32_b32 v254, -1, 0
	v_mbcnt_hi_u32_b32 v254, -1, v254
	v_lshlrev_b32_e32 v254, 7, v254
	global_load_dword v255, v254, s[18:19]
	s_add_u32 s18, s18, 0x2000
	s_addc_u32 s19, s19, 0
	global_load_dword v255, v254, s[18:19]
	s_add_u32 s18, s18, 0x2000
	s_addc_u32 s19, s19, 0
	global_load_dword v255, v254, s[18:19]
	s_mov_b64 exec, s[22:23]

.Lxb_pf_14:
	s_getpc_b64 s[18:19]
	s_mov_b64 s[22:23], exec
	s_mov_b64 exec, -1
	v_mbcnt_lo_u32_b32 v254, -1, 0
	v_mbcnt_hi_u32_b32 v254, -1, v254
	v_lshlrev_b32_e32 v254, 6, v254
	global_load_dword v255, v254, s[18:19]
	s_mov_b64 exec, s[22:23]
